# thin GEMM (phases 1, 8): first 27 K-loop loads issued ahead of the SSQ block in fresh registers, vmcnt waits of the MFMA section regenerated; on top of static wave priority
# baseline (speedup 1.0000x reference)
; __device__ __forceinline__ void thin_gemm(const bf16* XB, const bf16* WT, const float* SSQ, float* OUT, LAS unsigned char* lds) {
;     ...
;     for (int t0 = 2 * blockIdx.x; t0 < M / 16; t0 += 2 * gridDim.x) { const int tile = t0 + grp;
;         f32x4 acc = {0.f, 0.f, 0.f, 0.f};
;         const bf16* ap = XB + (size_t)(tile * 16 + fr) * DM + wk * 512 + q * 8; const bf16* bp = WT + (size_t)fr * DM + wk * 512 + q * 8;
;         float t4[4] = {0.f, 0.f, 0.f, 0.f};
;         if (wk == 0) {
; #pragma unroll
;             for (int i = 0; i < 4; ++i) { const f32x4* p = (const f32x4*)(SSQ + (size_t)(tile * 16 + 4 * q + i) * 32);
; #pragma unroll
;                 for (int j = 0; j < 8; ++j) { const f32x4 a = p[j]; t4[i] += (a[0] + a[1]) + (a[2] + a[3]); } } }
; #pragma unroll
;         for (int kb = 0; kb < 16; ++kb) { const bf16x8 a = *(const bf16x8*)(ap + kb * 32), b = *(const bf16x8*)(bp + kb * 32); acc = __builtin_amdgcn_mfma_f32_16x16x32_bf16(a, b, acc, 0, 0, 0); }
.LBB0_299:
	v_add_u32_e32 v76, v79, v81
	v_ashrrev_i32_e32 v77, 31, v76
	v_add_u32_e32 v74, 1, v76
	v_add_u32_e32 v72, 2, v76
	v_add_u32_e32 v70, 3, v76
	v_mov_b32_e32 v0, 0
	v_mov_b32_e32 v1, 0
	v_mov_b32_e32 v2, 0
	v_mov_b32_e32 v3, 0
	v_add_u32_e32 v254, v78, v81
	v_ashrrev_i32_e32 v255, 31, v254
	v_lshlrev_b64 v[254:255], 12, v[254:255]
	v_lshl_add_u64 v[250:251], v[64:65], 0, v[254:255]
	global_load_dwordx4 v[132:135], v[250:251], off
	global_load_dwordx4 v[136:139], v[250:251], off offset:64
	global_load_dwordx4 v[140:143], v[66:67], off
	global_load_dwordx4 v[144:147], v[66:67], off offset:64
	global_load_dwordx4 v[148:151], v[250:251], off offset:128
	global_load_dwordx4 v[152:155], v[250:251], off offset:192
	global_load_dwordx4 v[156:159], v[66:67], off offset:128
	global_load_dwordx4 v[160:163], v[66:67], off offset:192
	global_load_dwordx4 v[164:167], v[250:251], off offset:256
	global_load_dwordx4 v[168:171], v[250:251], off offset:320
	global_load_dwordx4 v[180:183], v[66:67], off offset:256
	global_load_dwordx4 v[184:187], v[66:67], off offset:320
	global_load_dwordx4 v[188:191], v[250:251], off offset:384
	global_load_dwordx4 v[192:195], v[66:67], off offset:384
	global_load_dwordx4 v[196:199], v[250:251], off offset:448
	global_load_dwordx4 v[200:203], v[66:67], off offset:448
	global_load_dwordx4 v[204:207], v[250:251], off offset:512
	global_load_dwordx4 v[208:211], v[250:251], off offset:576
	global_load_dwordx4 v[212:215], v[66:67], off offset:512
	global_load_dwordx4 v[216:219], v[66:67], off offset:576
	global_load_dwordx4 v[220:223], v[250:251], off offset:640
	global_load_dwordx4 v[224:227], v[66:67], off offset:640
	global_load_dwordx4 v[228:231], v[250:251], off offset:704
	global_load_dwordx4 v[232:235], v[66:67], off offset:704
	global_load_dwordx4 v[238:241], v[250:251], off offset:768
	global_load_dwordx4 v[242:245], v[66:67], off offset:768
	global_load_dwordx4 v[246:249], v[250:251], off offset:832
	s_and_saveexec_b64 s[0:1], s[6:7]
	s_cbranch_execz .LBB0_301
	v_readlane_b32 s2, v237, 48
	v_lshlrev_b64 v[0:1], 7, v[76:77]
	v_readlane_b32 s3, v237, 49
	v_ashrrev_i32_e32 v75, 31, v74
	v_ashrrev_i32_e32 v73, 31, v72
	v_lshl_add_u64 v[4:5], s[2:3], 0, v[0:1]
	global_load_dwordx4 v[60:63], v[4:5], off
	global_load_dwordx4 v[44:47], v[4:5], off offset:16
	global_load_dwordx4 v[28:31], v[4:5], off offset:32
	global_load_dwordx4 v[24:27], v[4:5], off offset:48
	global_load_dwordx4 v[16:19], v[4:5], off offset:80
	global_load_dwordx4 v[32:35], v[4:5], off offset:64
	v_lshlrev_b64 v[0:1], 7, v[74:75]
	s_waitcnt vmcnt(0)
	v_lshl_add_u64 v[12:13], s[2:3], 0, v[0:1]
	global_load_dwordx4 v[56:59], v[12:13], off
	global_load_dwordx4 v[48:51], v[12:13], off offset:16
	global_load_dwordx4 v[40:43], v[12:13], off offset:32
	global_load_dwordx4 v[36:39], v[12:13], off offset:48
	global_load_dwordx4 v[52:55], v[12:13], off offset:64
	global_load_dwordx4 v[20:23], v[12:13], off offset:80
	global_load_dwordx4 v[0:3], v[4:5], off offset:112
	global_load_dwordx4 v[8:11], v[4:5], off offset:96
	s_nop 0
	global_load_dwordx4 v[4:7], v[12:13], off offset:112
	s_nop 0
	global_load_dwordx4 v[12:15], v[12:13], off offset:96
	v_ashrrev_i32_e32 v71, 31, v70
	v_lshlrev_b64 v[86:87], 7, v[72:73]
	v_lshlrev_b64 v[88:89], 7, v[70:71]
	v_lshl_add_u64 v[114:115], s[2:3], 0, v[86:87]
	v_lshl_add_u64 v[126:127], s[2:3], 0, v[88:89]
	global_load_dwordx4 v[86:89], v[114:115], off offset:48
	global_load_dwordx4 v[90:93], v[114:115], off offset:32
	global_load_dwordx4 v[94:97], v[114:115], off offset:16
	global_load_dwordx4 v[98:101], v[114:115], off
	global_load_dwordx4 v[102:105], v[114:115], off offset:112
	global_load_dwordx4 v[106:109], v[114:115], off offset:96
	global_load_dwordx4 v[110:113], v[114:115], off offset:80
	s_nop 0
	global_load_dwordx4 v[114:117], v[114:115], off offset:64
	s_nop 0
	global_load_dwordx4 v[118:121], v[126:127], off
	global_load_dwordx4 v[122:125], v[126:127], off offset:16
	s_waitcnt vmcnt(19)
	v_mov_b32_e32 v131, v56
	v_mov_b32_e32 v130, v60
	v_mov_b32_e32 v60, v62
	v_mov_b32_e32 v56, v61
	v_mov_b32_e32 v61, v58
	v_mov_b32_e32 v58, v63
	v_mov_b32_e32 v62, v44
	v_mov_b32_e32 v44, v46
	v_mov_b32_e32 v46, v28
	v_mov_b32_e32 v28, v30
	v_mov_b32_e32 v30, v24
	v_mov_b32_e32 v24, v26
	v_mov_b32_e32 v26, v32
	v_mov_b32_e32 v32, v34
	v_mov_b32_e32 v34, v16
	s_waitcnt vmcnt(18)
	v_mov_b32_e32 v63, v48
	v_mov_b32_e32 v48, v45
	v_mov_b32_e32 v45, v50
	v_mov_b32_e32 v50, v47
	s_waitcnt vmcnt(17)
	v_mov_b32_e32 v47, v40
	v_mov_b32_e32 v40, v29
	v_mov_b32_e32 v29, v42
	v_mov_b32_e32 v42, v31
	s_waitcnt vmcnt(16)
	v_mov_b32_e32 v31, v36
	v_mov_b32_e32 v36, v25
	v_mov_b32_e32 v25, v38
	v_mov_b32_e32 v38, v27
	s_waitcnt vmcnt(15)
	v_mov_b32_e32 v27, v52
	v_mov_b32_e32 v52, v33
	v_mov_b32_e32 v33, v54
	v_mov_b32_e32 v54, v35
	s_waitcnt vmcnt(14)
	v_mov_b32_e32 v35, v20
	v_mov_b32_e32 v20, v17
	v_pk_add_f32 v[16:17], v[130:131], v[56:57]
	v_pk_add_f32 v[56:57], v[60:61], v[58:59]
	v_pk_add_f32 v[48:49], v[62:63], v[48:49]
	v_pk_add_f32 v[44:45], v[44:45], v[50:51]
	v_pk_add_f32 v[16:17], v[16:17], v[56:57]
	v_pk_add_f32 v[40:41], v[46:47], v[40:41]
	v_pk_add_f32 v[28:29], v[28:29], v[42:43]
	v_pk_add_f32 v[20:21], v[34:35], v[20:21]
	v_pk_add_f32 v[34:35], v[48:49], v[44:45]
	v_pk_add_f32 v[16:17], v[16:17], 0 op_sel_hi:[1,0]
	v_pk_add_f32 v[30:31], v[30:31], v[36:37]
	v_pk_add_f32 v[24:25], v[24:25], v[38:39]
	v_pk_add_f32 v[28:29], v[40:41], v[28:29]
	v_pk_add_f32 v[16:17], v[16:17], v[34:35]
	v_pk_add_f32 v[26:27], v[26:27], v[52:53]
	v_pk_add_f32 v[32:33], v[32:33], v[54:55]
	v_pk_add_f32 v[24:25], v[30:31], v[24:25]
	v_pk_add_f32 v[16:17], v[16:17], v[28:29]
	v_pk_add_f32 v[26:27], v[26:27], v[32:33]
	v_pk_add_f32 v[16:17], v[16:17], v[24:25]
	v_mov_b32_e32 v30, v18
	v_pk_add_f32 v[28:29], v[16:17], v[26:27]
	v_mov_b32_e32 v31, v22
	v_mov_b32_e32 v22, v19
	global_load_dwordx4 v[16:19], v[126:127], off offset:48
	global_load_dwordx4 v[24:27], v[126:127], off offset:32
	v_pk_add_f32 v[22:23], v[30:31], v[22:23]
	s_waitcnt vmcnt(14)
; __device__ __forceinline__ void thin_gemm(const bf16* XB, const bf16* WT, const float* SSQ, float* OUT, LAS unsigned char* lds) {
;     ...
;             for (int i = 0; i < 4; ++i) { const f32x4* p = (const f32x4*)(SSQ + (size_t)(tile * 16 + 4 * q + i) * 32);
; #pragma unroll
;                 for (int j = 0; j < 8; ++j) { const f32x4 a = p[j]; t4[i] += (a[0] + a[1]) + (a[2] + a[3]); } } }
	v_mov_b32_e32 v34, v8
	v_pk_add_f32 v[20:21], v[20:21], v[22:23]
	s_waitcnt vmcnt(12)
	v_mov_b32_e32 v35, v12
	v_pk_add_f32 v[32:33], v[28:29], v[20:21]
	global_load_dwordx4 v[20:23], v[126:127], off offset:80
	global_load_dwordx4 v[28:31], v[126:127], off offset:64
	v_mov_b32_e32 v12, v9
	v_pk_add_f32 v[8:9], v[34:35], v[12:13]
	v_mov_b32_e32 v12, v10
	v_mov_b32_e32 v13, v14
	v_mov_b32_e32 v14, v11
	v_pk_add_f32 v[10:11], v[12:13], v[14:15]
	v_mov_b32_e32 v34, v0
	v_pk_add_f32 v[8:9], v[8:9], v[10:11]
	v_mov_b32_e32 v35, v4
	v_pk_add_f32 v[32:33], v[32:33], v[8:9]
	global_load_dwordx4 v[8:11], v[126:127], off offset:112
	global_load_dwordx4 v[12:15], v[126:127], off offset:96
	v_mov_b32_e32 v4, v1
	v_pk_add_f32 v[0:1], v[34:35], v[4:5]
	v_mov_b32_e32 v4, v2
	v_mov_b32_e32 v5, v6
	v_mov_b32_e32 v6, v3
	v_pk_add_f32 v[2:3], v[4:5], v[6:7]
	s_waitcnt vmcnt(13)
	v_mov_b32_e32 v4, v95
	v_pk_add_f32 v[0:1], v[0:1], v[2:3]
	s_waitcnt vmcnt(12)
	v_mov_b32_e32 v2, v99
	v_mov_b32_e32 v3, v100
	v_mov_b32_e32 v99, v101
	v_mov_b32_e32 v5, v96
	v_mov_b32_e32 v95, v97
	v_pk_add_f32 v[2:3], v[2:3], v[98:99]
	v_pk_add_f32 v[4:5], v[4:5], v[94:95]
	v_add_f32_e32 v2, v2, v3
	v_pk_add_f32 v[4:5], v[4:5], v[4:5] op_sel:[0,1] op_sel_hi:[1,0]
	v_pk_add_f32 v[0:1], v[32:33], v[0:1]
	v_add_f32_e32 v2, 0, v2
	v_add_f32_e32 v6, v90, v91
	v_add_f32_e32 v32, v92, v93
	v_mov_b32_e32 v3, v86
	v_mov_b32_e32 v5, v87
	v_mov_b32_e32 v7, v88
	v_mov_b32_e32 v33, v89
	v_pk_add_f32 v[2:3], v[2:3], v[4:5]
	v_pk_add_f32 v[4:5], v[6:7], v[32:33]
	s_waitcnt vmcnt(9)
	v_add_f32_e32 v6, v110, v111
	v_pk_add_f32 v[2:3], v[2:3], v[4:5]
	s_waitcnt vmcnt(8)
	v_mov_b32_e32 v4, v115
	v_mov_b32_e32 v5, v116
	v_mov_b32_e32 v115, v117
	v_pk_add_f32 v[4:5], v[4:5], v[114:115]
	v_pk_add_f32 v[2:3], v[2:3], v[2:3] op_sel:[0,1] op_sel_hi:[1,0]
	v_pk_add_f32 v[4:5], v[4:5], v[4:5] op_sel:[0,1] op_sel_hi:[1,0]
	v_add_f32_e32 v32, v112, v113
	v_mov_b32_e32 v3, v106
	v_mov_b32_e32 v5, v107
	v_mov_b32_e32 v7, v108
	v_mov_b32_e32 v33, v109
	v_pk_add_f32 v[2:3], v[2:3], v[4:5]
	v_pk_add_f32 v[4:5], v[6:7], v[32:33]
	s_waitcnt vmcnt(7)
	v_mov_b32_e32 v6, v118
	s_waitcnt vmcnt(6)
	v_mov_b32_e32 v7, v122
	v_mov_b32_e32 v122, v119
	v_mov_b32_e32 v32, v120
	v_mov_b32_e32 v33, v124
	v_mov_b32_e32 v124, v121
	v_pk_add_f32 v[6:7], v[6:7], v[122:123]
	v_pk_add_f32 v[32:33], v[32:33], v[124:125]
	v_pk_add_f32 v[2:3], v[2:3], v[4:5]
	v_pk_add_f32 v[6:7], v[6:7], v[32:33]
	v_pk_add_f32 v[2:3], v[2:3], v[2:3] op_sel:[0,1] op_sel_hi:[1,0]
	v_mov_b32_e32 v4, v103
	v_add_f32_e32 v3, 0, v6
	v_add_f32_e32 v6, v3, v7
	v_mov_b32_e32 v5, v104
	v_mov_b32_e32 v103, v105
	v_pk_add_f32 v[4:5], v[4:5], v[102:103]
	s_waitcnt vmcnt(5)
	v_add_f32_e32 v16, v16, v17
	s_waitcnt vmcnt(4)
	v_mov_b32_e32 v32, v25
	v_mov_b32_e32 v33, v26
	v_mov_b32_e32 v25, v27
	v_pk_add_f32 v[24:25], v[32:33], v[24:25]
	v_add_f32_e32 v18, v18, v19
	v_pk_add_f32 v[24:25], v[24:25], v[24:25] op_sel:[0,1] op_sel_hi:[1,0]
	s_waitcnt vmcnt(2)
	v_mov_b32_e32 v7, v28
	v_mov_b32_e32 v25, v29
	v_mov_b32_e32 v17, v30
	v_mov_b32_e32 v19, v31
	v_pk_add_f32 v[6:7], v[6:7], v[24:25]
	v_pk_add_f32 v[16:17], v[16:17], v[18:19]
	v_pk_add_f32 v[4:5], v[4:5], v[4:5] op_sel:[0,1] op_sel_hi:[1,0]
	v_pk_add_f32 v[6:7], v[6:7], v[16:17]
	v_mov_b32_e32 v16, v21
	v_mov_b32_e32 v17, v22
	v_mov_b32_e32 v21, v23
	v_pk_add_f32 v[16:17], v[16:17], v[20:21]
	v_pk_add_f32 v[6:7], v[6:7], v[6:7] op_sel:[0,1] op_sel_hi:[1,0]
	v_pk_add_f32 v[16:17], v[16:17], v[16:17] op_sel:[0,1] op_sel_hi:[1,0]
	s_waitcnt vmcnt(0)
	v_add_f32_e32 v12, v12, v13
	v_add_f32_e32 v14, v14, v15
	v_mov_b32_e32 v7, v8
	v_mov_b32_e32 v17, v9
	v_mov_b32_e32 v13, v10
	v_mov_b32_e32 v15, v11
	v_pk_add_f32 v[6:7], v[6:7], v[16:17]
	v_pk_add_f32 v[8:9], v[12:13], v[14:15]
	s_nop 0
	v_pk_add_f32 v[6:7], v[6:7], v[8:9]
	s_nop 0
	v_mov_b32_e32 v3, v6
	v_mov_b32_e32 v5, v7
	v_pk_add_f32 v[2:3], v[2:3], v[4:5]
; __device__ __forceinline__ void thin_gemm(const bf16* XB, const bf16* WT, const float* SSQ, float* OUT, LAS unsigned char* lds) {
;     ...
;         for (int kb = 0; kb < 16; ++kb) { const bf16x8 a = *(const bf16x8*)(ap + kb * 32), b = *(const bf16x8*)(bp + kb * 32); acc = __builtin_amdgcn_mfma_f32_16x16x32_bf16(a, b, acc, 0, 0, 0); }
;         red[wave * 64 + lane] = acc;
;         __syncthreads();
;         if (wk == 0) {
;             f32x4 s = red[wave * 64 + lane];
; #pragma unroll
;             for (int w = 1; w < 4; ++w) s += red[(wave + w) * 64 + lane];
; #pragma unroll
;             for (int i = 0; i < 4; ++i) OUT[(size_t)(tile * 16 + 4 * q + i) * 16 + fr] = s[i] / sqrtf(t4[i] * (1.0f / 2048.0f) + 1e-6f);
;         }
;         __syncthreads();
.LBB0_301:
	s_or_b64 exec, exec, s[0:1]
	v_add_u32_e32 v4, v78, v81
	v_ashrrev_i32_e32 v5, 31, v4
	v_lshlrev_b64 v[4:5], 12, v[4:5]
	v_lshl_add_u64 v[52:53], v[64:65], 0, v[4:5]
	s_waitcnt vmcnt(24)
	v_mfma_f32_16x16x32_bf16 v[4:7], v[132:135], v[140:143], 0
	s_waitcnt vmcnt(23)
	v_mfma_f32_16x16x32_bf16 v[4:7], v[136:139], v[144:147], v[4:7]
	s_waitcnt vmcnt(20)
	v_mfma_f32_16x16x32_bf16 v[4:7], v[148:151], v[156:159], v[4:7]
	s_waitcnt vmcnt(19)
	v_mfma_f32_16x16x32_bf16 v[4:7], v[152:155], v[160:163], v[4:7]
	s_waitcnt vmcnt(16)
	v_mfma_f32_16x16x32_bf16 v[4:7], v[164:167], v[180:183], v[4:7]
	s_waitcnt vmcnt(15)
	v_mfma_f32_16x16x32_bf16 v[4:7], v[168:171], v[184:187], v[4:7]
	s_waitcnt vmcnt(13)
	v_mfma_f32_16x16x32_bf16 v[4:7], v[188:191], v[192:195], v[4:7]
	s_waitcnt vmcnt(11)
	v_mfma_f32_16x16x32_bf16 v[4:7], v[196:199], v[200:203], v[4:7]
	s_waitcnt vmcnt(8)
	v_mfma_f32_16x16x32_bf16 v[4:7], v[204:207], v[212:215], v[4:7]
	s_waitcnt vmcnt(7)
	v_mfma_f32_16x16x32_bf16 v[4:7], v[208:211], v[216:219], v[4:7]
	s_waitcnt vmcnt(5)
	v_mfma_f32_16x16x32_bf16 v[4:7], v[220:223], v[224:227], v[4:7]
	global_load_dwordx4 v[8:11], v[66:67], off offset:832
	s_waitcnt vmcnt(4)
	v_mfma_f32_16x16x32_bf16 v[4:7], v[228:231], v[232:235], v[4:7]
	global_load_dwordx4 v[12:15], v[52:53], off offset:896
	global_load_dwordx4 v[16:19], v[66:67], off offset:896
	s_waitcnt vmcnt(4)
	v_mfma_f32_16x16x32_bf16 v[4:7], v[238:241], v[242:245], v[4:7]
	global_load_dwordx4 v[20:23], v[52:53], off offset:960
	s_waitcnt vmcnt(3)
	v_mfma_f32_16x16x32_bf16 v[4:7], v[246:249], v[8:11], v[4:7]
	global_load_dwordx4 v[8:11], v[66:67], off offset:960
	s_waitcnt vmcnt(2)
	v_mfma_f32_16x16x32_bf16 v[4:7], v[12:15], v[16:19], v[4:7]
	s_waitcnt vmcnt(0)
	v_mfma_f32_16x16x32_bf16 v[4:7], v[20:23], v[8:11], v[4:7]
	s_nop 7
	ds_write_b128 v80, v[4:7]
	s_waitcnt lgkmcnt(0)
	s_barrier
	s_and_saveexec_b64 s[2:3], s[6:7]
	s_cbranch_execz .LBB0_298
	v_fmamk_f32 v0, v0, 0x3a000000, v83
	v_mul_f32_e32 v20, 0x4f800000, v0
	v_cmp_gt_f32_e32 vcc, s12, v0
	ds_read_b128 v[4:7], v80
	ds_read_b128 v[8:11], v82 offset:1024
	ds_read_b128 v[12:15], v82 offset:2048
	ds_read_b128 v[16:19], v82 offset:3072
	v_cndmask_b32_e32 v0, v0, v20, vcc
	v_sqrt_f32_e32 v20, v0
	s_waitcnt lgkmcnt(2)
	v_pk_add_f32 v[4:5], v[4:5], v[8:9]
	v_pk_add_f32 v[6:7], v[6:7], v[10:11]
	s_waitcnt lgkmcnt(1)
	v_pk_add_f32 v[4:5], v[4:5], v[12:13]
	v_add_u32_e32 v8, -1, v20
	v_fma_f32 v9, -v8, v20, v0
	v_cmp_ge_f32_e64 s[0:1], 0, v9
	v_add_u32_e32 v9, 1, v20
	v_fma_f32 v12, -v9, v20, v0
	v_cndmask_b32_e64 v8, v20, v8, s[0:1]
	v_cmp_lt_f32_e64 s[0:1], 0, v12
	s_waitcnt lgkmcnt(0)
	v_pk_add_f32 v[4:5], v[4:5], v[16:17]
	v_fmamk_f32 v1, v1, 0x3a000000, v83
	v_cndmask_b32_e64 v8, v8, v9, s[0:1]
	v_mul_f32_e32 v9, 0x37800000, v8
	v_cndmask_b32_e32 v8, v8, v9, vcc
	v_cmp_class_f32_e32 vcc, v0, v84
	v_fmamk_f32 v2, v2, 0x3a000000, v83
	v_pk_add_f32 v[6:7], v[6:7], v[14:15]
	v_cndmask_b32_e32 v0, v8, v0, vcc
	v_div_scale_f32 v8, s[0:1], v0, v0, v4
	v_rcp_f32_e32 v9, v8
	v_cmp_gt_f32_e64 s[0:1], s12, v1
	v_pk_add_f32 v[6:7], v[6:7], v[18:19]
	v_ashrrev_i32_e32 v75, 31, v74
	v_fma_f32 v10, -v8, v9, 1.0
	v_fmac_f32_e32 v9, v10, v9
	v_div_scale_f32 v10, vcc, v4, v0, v4
	v_mul_f32_e32 v11, v10, v9
	v_fma_f32 v12, -v8, v11, v10
	v_fmac_f32_e32 v11, v12, v9
	v_fma_f32 v8, -v8, v11, v10
	v_mul_f32_e32 v10, 0x4f800000, v1
	v_cndmask_b32_e64 v1, v1, v10, s[0:1]
	v_sqrt_f32_e32 v10, v1
	v_div_fmas_f32 v8, v8, v9, v11
	v_div_fixup_f32 v4, v8, v0, v4
	v_fmamk_f32 v3, v3, 0x3a000000, v83
	v_add_u32_e32 v0, -1, v10
	v_fma_f32 v8, -v0, v10, v1
	v_cmp_ge_f32_e32 vcc, 0, v8
	v_add_u32_e32 v8, 1, v10
	v_fma_f32 v9, -v8, v10, v1
	v_cndmask_b32_e32 v0, v10, v0, vcc
	v_cmp_lt_f32_e32 vcc, 0, v9
	v_ashrrev_i32_e32 v73, 31, v72
	v_ashrrev_i32_e32 v71, 31, v70
	v_cndmask_b32_e32 v0, v0, v8, vcc
	v_mul_f32_e32 v8, 0x37800000, v0
	v_cndmask_b32_e64 v0, v0, v8, s[0:1]
	v_cmp_class_f32_e32 vcc, v1, v84
	s_nop 1
	v_cndmask_b32_e32 v8, v0, v1, vcc
	v_div_scale_f32 v9, s[0:1], v8, v8, v5
	v_rcp_f32_e32 v10, v9
	v_lshlrev_b64 v[0:1], 6, v[76:77]
	v_lshl_add_u64 v[0:1], v[68:69], 0, v[0:1]
	global_store_dword v[0:1], v4, off
	v_fma_f32 v0, -v9, v10, 1.0
	v_fmac_f32_e32 v10, v0, v10
	v_div_scale_f32 v0, vcc, v5, v8, v5
	v_mul_f32_e32 v1, v0, v10
	v_fma_f32 v4, -v9, v1, v0
	v_fmac_f32_e32 v1, v4, v10
	v_mul_f32_e32 v4, 0x4f800000, v2
	v_cmp_gt_f32_e64 s[0:1], s12, v2
	v_fma_f32 v0, -v9, v1, v0
	v_div_fmas_f32 v0, v0, v10, v1
	v_cndmask_b32_e64 v2, v2, v4, s[0:1]
	v_sqrt_f32_e32 v4, v2
	v_div_fixup_f32 v5, v0, v8, v5
	v_add_u32_e32 v0, -1, v4
	v_fma_f32 v1, -v0, v4, v2
	v_cmp_ge_f32_e32 vcc, 0, v1
	v_add_u32_e32 v1, 1, v4
	s_nop 0
	v_cndmask_b32_e32 v0, v4, v0, vcc
	v_fma_f32 v4, -v1, v4, v2
	v_cmp_lt_f32_e32 vcc, 0, v4
	s_nop 1
	v_cndmask_b32_e32 v0, v0, v1, vcc
	v_mul_f32_e32 v1, 0x37800000, v0
	v_cndmask_b32_e64 v0, v0, v1, s[0:1]
	v_cmp_class_f32_e32 vcc, v2, v84
	s_nop 1
	v_cndmask_b32_e32 v2, v0, v2, vcc
	v_div_scale_f32 v4, s[0:1], v2, v2, v6
	v_rcp_f32_e32 v8, v4
	v_lshlrev_b64 v[0:1], 6, v[74:75]
	v_lshl_add_u64 v[0:1], v[68:69], 0, v[0:1]
	global_store_dword v[0:1], v5, off
	v_fma_f32 v0, -v4, v8, 1.0
	v_fmac_f32_e32 v8, v0, v8
	v_div_scale_f32 v0, vcc, v6, v2, v6
	v_mul_f32_e32 v1, v0, v8
	v_fma_f32 v5, -v4, v1, v0
	v_fmac_f32_e32 v1, v5, v8
	v_fma_f32 v0, -v4, v1, v0
	v_mul_f32_e32 v4, 0x4f800000, v3
	v_cmp_gt_f32_e64 s[0:1], s12, v3
	v_div_fmas_f32 v0, v0, v8, v1
	v_div_fixup_f32 v2, v0, v2, v6
	v_cndmask_b32_e64 v3, v3, v4, s[0:1]
	v_sqrt_f32_e32 v4, v3
	s_nop 0
	v_add_u32_e32 v0, -1, v4
	v_fma_f32 v1, -v0, v4, v3
	v_cmp_ge_f32_e32 vcc, 0, v1
	v_add_u32_e32 v1, 1, v4
	s_nop 0
	v_cndmask_b32_e32 v0, v4, v0, vcc
	v_fma_f32 v4, -v1, v4, v3
	v_cmp_lt_f32_e32 vcc, 0, v4
	s_nop 1
	v_cndmask_b32_e32 v0, v0, v1, vcc
	v_mul_f32_e32 v1, 0x37800000, v0
	v_cndmask_b32_e64 v0, v0, v1, s[0:1]
	v_cmp_class_f32_e32 vcc, v3, v84
	s_nop 1
	v_cndmask_b32_e32 v3, v0, v3, vcc
	v_div_scale_f32 v4, s[0:1], v3, v3, v7
	v_rcp_f32_e32 v5, v4
	v_lshlrev_b64 v[0:1], 6, v[72:73]
	v_lshl_add_u64 v[0:1], v[68:69], 0, v[0:1]
	global_store_dword v[0:1], v2, off
	v_fma_f32 v0, -v4, v5, 1.0
	v_fmac_f32_e32 v5, v0, v5
	v_div_scale_f32 v0, vcc, v7, v3, v7
	v_mul_f32_e32 v1, v0, v5
	v_fma_f32 v2, -v4, v1, v0
	v_fmac_f32_e32 v1, v2, v5
	v_fma_f32 v0, -v4, v1, v0
	v_div_fmas_f32 v0, v0, v5, v1
	v_div_fixup_f32 v2, v0, v3, v7
	v_lshlrev_b64 v[0:1], 6, v[70:71]
	v_lshl_add_u64 v[0:1], v[68:69], 0, v[0:1]
	global_store_dword v[0:1], v2, off
	s_branch .LBB0_298

; __device__ __forceinline__ void thin_gemm(const bf16* XB, const bf16* WT, const float* SSQ, float* OUT, LAS unsigned char* lds) {
;     ...
;     for (int t0 = 2 * blockIdx.x; t0 < M / 16; t0 += 2 * gridDim.x) { const int tile = t0 + grp;
;         f32x4 acc = {0.f, 0.f, 0.f, 0.f};
;         const bf16* ap = XB + (size_t)(tile * 16 + fr) * DM + wk * 512 + q * 8; const bf16* bp = WT + (size_t)fr * DM + wk * 512 + q * 8;
;         float t4[4] = {0.f, 0.f, 0.f, 0.f};
;         if (wk == 0) {
; #pragma unroll
;             for (int i = 0; i < 4; ++i) { const f32x4* p = (const f32x4*)(SSQ + (size_t)(tile * 16 + 4 * q + i) * 32);
; #pragma unroll
;                 for (int j = 0; j < 8; ++j) { const f32x4 a = p[j]; t4[i] += (a[0] + a[1]) + (a[2] + a[3]); } } }
.LBB0_1191:
	v_add_u32_e32 v76, v79, v81
	v_ashrrev_i32_e32 v77, 31, v76
	v_add_u32_e32 v74, 1, v76
	v_add_u32_e32 v72, 2, v76
	v_add_u32_e32 v70, 3, v76
	v_mov_b32_e32 v0, 0
	v_mov_b32_e32 v1, 0
	v_mov_b32_e32 v2, 0
	v_mov_b32_e32 v3, 0
	v_add_u32_e32 v254, v78, v81
	v_ashrrev_i32_e32 v255, 31, v254
	v_lshlrev_b64 v[254:255], 12, v[254:255]
	v_lshl_add_u64 v[250:251], v[64:65], 0, v[254:255]
	global_load_dwordx4 v[132:135], v[250:251], off
	global_load_dwordx4 v[136:139], v[250:251], off offset:64
	global_load_dwordx4 v[140:143], v[66:67], off
	global_load_dwordx4 v[144:147], v[66:67], off offset:64
	global_load_dwordx4 v[148:151], v[250:251], off offset:128
	global_load_dwordx4 v[152:155], v[250:251], off offset:192
	global_load_dwordx4 v[156:159], v[66:67], off offset:128
	global_load_dwordx4 v[160:163], v[66:67], off offset:192
	global_load_dwordx4 v[164:167], v[250:251], off offset:256
	global_load_dwordx4 v[168:171], v[250:251], off offset:320
	global_load_dwordx4 v[180:183], v[66:67], off offset:256
	global_load_dwordx4 v[184:187], v[66:67], off offset:320
	global_load_dwordx4 v[188:191], v[250:251], off offset:384
	global_load_dwordx4 v[192:195], v[66:67], off offset:384
	global_load_dwordx4 v[196:199], v[250:251], off offset:448
	global_load_dwordx4 v[200:203], v[66:67], off offset:448
	global_load_dwordx4 v[204:207], v[250:251], off offset:512
	global_load_dwordx4 v[208:211], v[250:251], off offset:576
	global_load_dwordx4 v[212:215], v[66:67], off offset:512
	global_load_dwordx4 v[216:219], v[66:67], off offset:576
	global_load_dwordx4 v[220:223], v[250:251], off offset:640
	global_load_dwordx4 v[224:227], v[66:67], off offset:640
	global_load_dwordx4 v[228:231], v[250:251], off offset:704
	global_load_dwordx4 v[232:235], v[66:67], off offset:704
	global_load_dwordx4 v[238:241], v[250:251], off offset:768
	global_load_dwordx4 v[242:245], v[66:67], off offset:768
	global_load_dwordx4 v[246:249], v[250:251], off offset:832
	s_and_saveexec_b64 s[0:1], s[8:9]
	s_cbranch_execz .LBB0_1193
	v_readlane_b32 s2, v237, 48
	v_lshlrev_b64 v[0:1], 7, v[76:77]
	v_readlane_b32 s3, v237, 49
	v_ashrrev_i32_e32 v75, 31, v74
	v_ashrrev_i32_e32 v73, 31, v72
	v_lshl_add_u64 v[4:5], s[2:3], 0, v[0:1]
	global_load_dwordx4 v[60:63], v[4:5], off
	global_load_dwordx4 v[44:47], v[4:5], off offset:16
	global_load_dwordx4 v[28:31], v[4:5], off offset:32
	global_load_dwordx4 v[24:27], v[4:5], off offset:48
	global_load_dwordx4 v[16:19], v[4:5], off offset:80
	global_load_dwordx4 v[32:35], v[4:5], off offset:64
	v_lshlrev_b64 v[0:1], 7, v[74:75]
	v_lshl_add_u64 v[12:13], s[2:3], 0, v[0:1]
	global_load_dwordx4 v[56:59], v[12:13], off
	global_load_dwordx4 v[48:51], v[12:13], off offset:16
	global_load_dwordx4 v[40:43], v[12:13], off offset:32
	global_load_dwordx4 v[36:39], v[12:13], off offset:48
	global_load_dwordx4 v[52:55], v[12:13], off offset:64
	global_load_dwordx4 v[20:23], v[12:13], off offset:80
	global_load_dwordx4 v[0:3], v[4:5], off offset:112
	global_load_dwordx4 v[8:11], v[4:5], off offset:96
	s_nop 0
	global_load_dwordx4 v[4:7], v[12:13], off offset:112
	s_nop 0
	global_load_dwordx4 v[12:15], v[12:13], off offset:96
	v_ashrrev_i32_e32 v71, 31, v70
	v_lshlrev_b64 v[86:87], 7, v[72:73]
	v_lshlrev_b64 v[88:89], 7, v[70:71]
	v_lshl_add_u64 v[114:115], s[2:3], 0, v[86:87]
	v_lshl_add_u64 v[126:127], s[2:3], 0, v[88:89]
	global_load_dwordx4 v[86:89], v[114:115], off offset:48
	global_load_dwordx4 v[90:93], v[114:115], off offset:32
	global_load_dwordx4 v[94:97], v[114:115], off offset:16
	global_load_dwordx4 v[98:101], v[114:115], off
	global_load_dwordx4 v[102:105], v[114:115], off offset:112
	global_load_dwordx4 v[106:109], v[114:115], off offset:96
	global_load_dwordx4 v[110:113], v[114:115], off offset:80
	s_nop 0
	global_load_dwordx4 v[114:117], v[114:115], off offset:64
	s_nop 0
	global_load_dwordx4 v[118:121], v[126:127], off
	global_load_dwordx4 v[122:125], v[126:127], off offset:16
	s_waitcnt vmcnt(0)
	v_mov_b32_e32 v131, v56
	v_mov_b32_e32 v130, v60
	v_mov_b32_e32 v60, v62
	v_mov_b32_e32 v56, v61
	v_mov_b32_e32 v61, v58
	v_mov_b32_e32 v58, v63
	v_mov_b32_e32 v62, v44
	v_mov_b32_e32 v44, v46
	v_mov_b32_e32 v46, v28
	v_mov_b32_e32 v28, v30
	v_mov_b32_e32 v30, v24
	v_mov_b32_e32 v24, v26
	v_mov_b32_e32 v26, v32
	v_mov_b32_e32 v32, v34
	v_mov_b32_e32 v34, v16
	v_mov_b32_e32 v63, v48
	v_mov_b32_e32 v48, v45
	v_mov_b32_e32 v45, v50
	v_mov_b32_e32 v50, v47
	v_mov_b32_e32 v47, v40
	v_mov_b32_e32 v40, v29
	v_mov_b32_e32 v29, v42
	v_mov_b32_e32 v42, v31
	v_mov_b32_e32 v31, v36
	v_mov_b32_e32 v36, v25
	v_mov_b32_e32 v25, v38
	v_mov_b32_e32 v38, v27
	v_mov_b32_e32 v27, v52
	v_mov_b32_e32 v52, v33
	v_mov_b32_e32 v33, v54
	v_mov_b32_e32 v54, v35
	v_mov_b32_e32 v35, v20
	v_mov_b32_e32 v20, v17
	v_pk_add_f32 v[16:17], v[130:131], v[56:57]
	v_pk_add_f32 v[56:57], v[60:61], v[58:59]
	v_pk_add_f32 v[48:49], v[62:63], v[48:49]
	v_pk_add_f32 v[44:45], v[44:45], v[50:51]
	v_pk_add_f32 v[16:17], v[16:17], v[56:57]
	v_pk_add_f32 v[40:41], v[46:47], v[40:41]
	v_pk_add_f32 v[28:29], v[28:29], v[42:43]
	v_pk_add_f32 v[20:21], v[34:35], v[20:21]
	v_pk_add_f32 v[34:35], v[48:49], v[44:45]
	v_pk_add_f32 v[16:17], v[16:17], 0 op_sel_hi:[1,0]
	v_pk_add_f32 v[30:31], v[30:31], v[36:37]
	v_pk_add_f32 v[24:25], v[24:25], v[38:39]
	v_pk_add_f32 v[28:29], v[40:41], v[28:29]
	v_pk_add_f32 v[16:17], v[16:17], v[34:35]
	v_pk_add_f32 v[26:27], v[26:27], v[52:53]
	v_pk_add_f32 v[32:33], v[32:33], v[54:55]
	v_pk_add_f32 v[24:25], v[30:31], v[24:25]
	v_pk_add_f32 v[16:17], v[16:17], v[28:29]
	v_pk_add_f32 v[26:27], v[26:27], v[32:33]
	v_pk_add_f32 v[16:17], v[16:17], v[24:25]
; __device__ __forceinline__ void thin_gemm(const bf16* XB, const bf16* WT, const float* SSQ, float* OUT, LAS unsigned char* lds) {
;     ...
;             for (int i = 0; i < 4; ++i) { const f32x4* p = (const f32x4*)(SSQ + (size_t)(tile * 16 + 4 * q + i) * 32);
; #pragma unroll
;                 for (int j = 0; j < 8; ++j) { const f32x4 a = p[j]; t4[i] += (a[0] + a[1]) + (a[2] + a[3]); } } }
	v_mov_b32_e32 v30, v18
	v_pk_add_f32 v[28:29], v[16:17], v[26:27]
	v_mov_b32_e32 v31, v22
	v_mov_b32_e32 v22, v19
	global_load_dwordx4 v[16:19], v[126:127], off offset:48
	global_load_dwordx4 v[24:27], v[126:127], off offset:32
	v_pk_add_f32 v[22:23], v[30:31], v[22:23]
	v_mov_b32_e32 v34, v8
	v_pk_add_f32 v[20:21], v[20:21], v[22:23]
	v_mov_b32_e32 v35, v12
	v_pk_add_f32 v[32:33], v[28:29], v[20:21]
	global_load_dwordx4 v[20:23], v[126:127], off offset:80
	global_load_dwordx4 v[28:31], v[126:127], off offset:64
	v_mov_b32_e32 v12, v9
	v_pk_add_f32 v[8:9], v[34:35], v[12:13]
	v_mov_b32_e32 v12, v10
	v_mov_b32_e32 v13, v14
	v_mov_b32_e32 v14, v11
	v_pk_add_f32 v[10:11], v[12:13], v[14:15]
	v_mov_b32_e32 v34, v0
	v_pk_add_f32 v[8:9], v[8:9], v[10:11]
	v_mov_b32_e32 v35, v4
	v_pk_add_f32 v[32:33], v[32:33], v[8:9]
	global_load_dwordx4 v[8:11], v[126:127], off offset:112
	global_load_dwordx4 v[12:15], v[126:127], off offset:96
	v_mov_b32_e32 v4, v1
	v_pk_add_f32 v[0:1], v[34:35], v[4:5]
	v_mov_b32_e32 v4, v2
	v_mov_b32_e32 v5, v6
	v_mov_b32_e32 v6, v3
	v_pk_add_f32 v[2:3], v[4:5], v[6:7]
	v_mov_b32_e32 v4, v95
	v_pk_add_f32 v[0:1], v[0:1], v[2:3]
	v_mov_b32_e32 v2, v99
	v_mov_b32_e32 v3, v100
	v_mov_b32_e32 v99, v101
	v_mov_b32_e32 v5, v96
	v_mov_b32_e32 v95, v97
	v_pk_add_f32 v[2:3], v[2:3], v[98:99]
	v_pk_add_f32 v[4:5], v[4:5], v[94:95]
	v_add_f32_e32 v2, v2, v3
	v_pk_add_f32 v[4:5], v[4:5], v[4:5] op_sel:[0,1] op_sel_hi:[1,0]
	v_pk_add_f32 v[0:1], v[32:33], v[0:1]
	v_add_f32_e32 v2, 0, v2
	v_add_f32_e32 v6, v90, v91
	v_add_f32_e32 v32, v92, v93
	v_mov_b32_e32 v3, v86
	v_mov_b32_e32 v5, v87
	v_mov_b32_e32 v7, v88
	v_mov_b32_e32 v33, v89
	v_pk_add_f32 v[2:3], v[2:3], v[4:5]
	v_pk_add_f32 v[4:5], v[6:7], v[32:33]
	v_add_f32_e32 v6, v110, v111
	v_pk_add_f32 v[2:3], v[2:3], v[4:5]
	v_mov_b32_e32 v4, v115
	v_mov_b32_e32 v5, v116
	v_mov_b32_e32 v115, v117
	v_pk_add_f32 v[4:5], v[4:5], v[114:115]
	v_pk_add_f32 v[2:3], v[2:3], v[2:3] op_sel:[0,1] op_sel_hi:[1,0]
	v_pk_add_f32 v[4:5], v[4:5], v[4:5] op_sel:[0,1] op_sel_hi:[1,0]
	v_add_f32_e32 v32, v112, v113
	v_mov_b32_e32 v3, v106
	v_mov_b32_e32 v5, v107
	v_mov_b32_e32 v7, v108
	v_mov_b32_e32 v33, v109
	v_pk_add_f32 v[2:3], v[2:3], v[4:5]
	v_pk_add_f32 v[4:5], v[6:7], v[32:33]
	v_mov_b32_e32 v6, v118
	v_mov_b32_e32 v7, v122
	v_mov_b32_e32 v122, v119
	v_mov_b32_e32 v32, v120
	v_mov_b32_e32 v33, v124
	v_mov_b32_e32 v124, v121
	v_pk_add_f32 v[6:7], v[6:7], v[122:123]
	v_pk_add_f32 v[32:33], v[32:33], v[124:125]
	v_pk_add_f32 v[2:3], v[2:3], v[4:5]
	v_pk_add_f32 v[6:7], v[6:7], v[32:33]
	v_pk_add_f32 v[2:3], v[2:3], v[2:3] op_sel:[0,1] op_sel_hi:[1,0]
	v_mov_b32_e32 v4, v103
	v_add_f32_e32 v3, 0, v6
	v_add_f32_e32 v6, v3, v7
	v_mov_b32_e32 v5, v104
	v_mov_b32_e32 v103, v105
	v_pk_add_f32 v[4:5], v[4:5], v[102:103]
	s_waitcnt vmcnt(5)
	v_add_f32_e32 v16, v16, v17
	s_waitcnt vmcnt(4)
	v_mov_b32_e32 v32, v25
	v_mov_b32_e32 v33, v26
	v_mov_b32_e32 v25, v27
	v_pk_add_f32 v[24:25], v[32:33], v[24:25]
	v_add_f32_e32 v18, v18, v19
	v_pk_add_f32 v[24:25], v[24:25], v[24:25] op_sel:[0,1] op_sel_hi:[1,0]
	s_waitcnt vmcnt(2)
	v_mov_b32_e32 v7, v28
	v_mov_b32_e32 v25, v29
	v_mov_b32_e32 v17, v30
	v_mov_b32_e32 v19, v31
	v_pk_add_f32 v[6:7], v[6:7], v[24:25]
	v_pk_add_f32 v[16:17], v[16:17], v[18:19]
	v_pk_add_f32 v[4:5], v[4:5], v[4:5] op_sel:[0,1] op_sel_hi:[1,0]
	v_pk_add_f32 v[6:7], v[6:7], v[16:17]
	v_mov_b32_e32 v16, v21
	v_mov_b32_e32 v17, v22
	v_mov_b32_e32 v21, v23
	v_pk_add_f32 v[16:17], v[16:17], v[20:21]
	v_pk_add_f32 v[6:7], v[6:7], v[6:7] op_sel:[0,1] op_sel_hi:[1,0]
	v_pk_add_f32 v[16:17], v[16:17], v[16:17] op_sel:[0,1] op_sel_hi:[1,0]
	s_waitcnt vmcnt(0)
	v_add_f32_e32 v12, v12, v13
	v_add_f32_e32 v14, v14, v15
	v_mov_b32_e32 v7, v8
	v_mov_b32_e32 v17, v9
	v_mov_b32_e32 v13, v10
	v_mov_b32_e32 v15, v11
	v_pk_add_f32 v[6:7], v[6:7], v[16:17]
	v_pk_add_f32 v[8:9], v[12:13], v[14:15]
	s_nop 0
	v_pk_add_f32 v[6:7], v[6:7], v[8:9]
	s_nop 0
	v_mov_b32_e32 v3, v6
	v_mov_b32_e32 v5, v7
	v_pk_add_f32 v[2:3], v[2:3], v[4:5]
; __device__ __forceinline__ void thin_gemm(const bf16* XB, const bf16* WT, const float* SSQ, float* OUT, LAS unsigned char* lds) {
;     ...
;         for (int kb = 0; kb < 16; ++kb) { const bf16x8 a = *(const bf16x8*)(ap + kb * 32), b = *(const bf16x8*)(bp + kb * 32); acc = __builtin_amdgcn_mfma_f32_16x16x32_bf16(a, b, acc, 0, 0, 0); }
;         red[wave * 64 + lane] = acc;
;         __syncthreads();
;         if (wk == 0) {
;             f32x4 s = red[wave * 64 + lane];
; #pragma unroll
;             for (int w = 1; w < 4; ++w) s += red[(wave + w) * 64 + lane];
; #pragma unroll
;             for (int i = 0; i < 4; ++i) OUT[(size_t)(tile * 16 + 4 * q + i) * 16 + fr] = s[i] / sqrtf(t4[i] * (1.0f / 2048.0f) + 1e-6f);
;         }
;         __syncthreads();
.LBB0_1193:
	s_or_b64 exec, exec, s[0:1]
	v_add_u32_e32 v4, v78, v81
	v_ashrrev_i32_e32 v5, 31, v4
	v_lshlrev_b64 v[4:5], 12, v[4:5]
	v_lshl_add_u64 v[52:53], v[64:65], 0, v[4:5]
	s_waitcnt vmcnt(24)
	v_mfma_f32_16x16x32_bf16 v[4:7], v[132:135], v[140:143], 0
	s_waitcnt vmcnt(23)
	v_mfma_f32_16x16x32_bf16 v[4:7], v[136:139], v[144:147], v[4:7]
	s_waitcnt vmcnt(20)
	v_mfma_f32_16x16x32_bf16 v[4:7], v[148:151], v[156:159], v[4:7]
	s_waitcnt vmcnt(19)
	v_mfma_f32_16x16x32_bf16 v[4:7], v[152:155], v[160:163], v[4:7]
	s_waitcnt vmcnt(16)
	v_mfma_f32_16x16x32_bf16 v[4:7], v[164:167], v[180:183], v[4:7]
	s_waitcnt vmcnt(15)
	v_mfma_f32_16x16x32_bf16 v[4:7], v[168:171], v[184:187], v[4:7]
	s_waitcnt vmcnt(13)
	v_mfma_f32_16x16x32_bf16 v[4:7], v[188:191], v[192:195], v[4:7]
	s_waitcnt vmcnt(11)
	v_mfma_f32_16x16x32_bf16 v[4:7], v[196:199], v[200:203], v[4:7]
	s_waitcnt vmcnt(8)
	v_mfma_f32_16x16x32_bf16 v[4:7], v[204:207], v[212:215], v[4:7]
	s_waitcnt vmcnt(7)
	v_mfma_f32_16x16x32_bf16 v[4:7], v[208:211], v[216:219], v[4:7]
	s_waitcnt vmcnt(5)
	v_mfma_f32_16x16x32_bf16 v[4:7], v[220:223], v[224:227], v[4:7]
	global_load_dwordx4 v[8:11], v[66:67], off offset:832
	s_waitcnt vmcnt(4)
	v_mfma_f32_16x16x32_bf16 v[4:7], v[228:231], v[232:235], v[4:7]
	global_load_dwordx4 v[12:15], v[52:53], off offset:896
	global_load_dwordx4 v[16:19], v[66:67], off offset:896
	s_waitcnt vmcnt(4)
	v_mfma_f32_16x16x32_bf16 v[4:7], v[238:241], v[242:245], v[4:7]
	global_load_dwordx4 v[20:23], v[52:53], off offset:960
	s_waitcnt vmcnt(3)
	v_mfma_f32_16x16x32_bf16 v[4:7], v[246:249], v[8:11], v[4:7]
	global_load_dwordx4 v[8:11], v[66:67], off offset:960
	s_waitcnt vmcnt(2)
	v_mfma_f32_16x16x32_bf16 v[4:7], v[12:15], v[16:19], v[4:7]
	s_waitcnt vmcnt(0)
	v_mfma_f32_16x16x32_bf16 v[4:7], v[20:23], v[8:11], v[4:7]
	s_nop 7
	ds_write_b128 v80, v[4:7]
	s_waitcnt lgkmcnt(0)
	s_barrier
	s_and_saveexec_b64 s[2:3], s[8:9]
	s_cbranch_execz .LBB0_1190
	v_fmamk_f32 v0, v0, 0x3a000000, v83
	v_mul_f32_e32 v20, 0x4f800000, v0
	v_cmp_gt_f32_e32 vcc, s6, v0
	ds_read_b128 v[4:7], v80
	ds_read_b128 v[8:11], v82 offset:1024
	ds_read_b128 v[12:15], v82 offset:2048
	ds_read_b128 v[16:19], v82 offset:3072
	v_cndmask_b32_e32 v0, v0, v20, vcc
	v_sqrt_f32_e32 v20, v0
	s_waitcnt lgkmcnt(2)
	v_pk_add_f32 v[4:5], v[4:5], v[8:9]
	v_pk_add_f32 v[6:7], v[6:7], v[10:11]
	s_waitcnt lgkmcnt(1)
	v_pk_add_f32 v[4:5], v[4:5], v[12:13]
	v_add_u32_e32 v8, -1, v20
	v_fma_f32 v9, -v8, v20, v0
	v_cmp_ge_f32_e64 s[0:1], 0, v9
	v_add_u32_e32 v9, 1, v20
	v_fma_f32 v12, -v9, v20, v0
	v_cndmask_b32_e64 v8, v20, v8, s[0:1]
	v_cmp_lt_f32_e64 s[0:1], 0, v12
	s_waitcnt lgkmcnt(0)
	v_pk_add_f32 v[4:5], v[4:5], v[16:17]
	v_fmamk_f32 v1, v1, 0x3a000000, v83
	v_cndmask_b32_e64 v8, v8, v9, s[0:1]
	v_mul_f32_e32 v9, 0x37800000, v8
	v_cndmask_b32_e32 v8, v8, v9, vcc
	v_cmp_class_f32_e32 vcc, v0, v84
	v_fmamk_f32 v2, v2, 0x3a000000, v83
	v_pk_add_f32 v[6:7], v[6:7], v[14:15]
	v_cndmask_b32_e32 v0, v8, v0, vcc
	v_div_scale_f32 v8, s[0:1], v0, v0, v4
	v_rcp_f32_e32 v9, v8
	v_cmp_gt_f32_e64 s[0:1], s6, v1
	v_pk_add_f32 v[6:7], v[6:7], v[18:19]
	v_ashrrev_i32_e32 v75, 31, v74
	v_fma_f32 v10, -v8, v9, 1.0
	v_fmac_f32_e32 v9, v10, v9
	v_div_scale_f32 v10, vcc, v4, v0, v4
	v_mul_f32_e32 v11, v10, v9
	v_fma_f32 v12, -v8, v11, v10
	v_fmac_f32_e32 v11, v12, v9
	v_fma_f32 v8, -v8, v11, v10
	v_mul_f32_e32 v10, 0x4f800000, v1
	v_cndmask_b32_e64 v1, v1, v10, s[0:1]
	v_sqrt_f32_e32 v10, v1
	v_div_fmas_f32 v8, v8, v9, v11
	v_div_fixup_f32 v4, v8, v0, v4
	v_fmamk_f32 v3, v3, 0x3a000000, v83
	v_add_u32_e32 v0, -1, v10
	v_fma_f32 v8, -v0, v10, v1
	v_cmp_ge_f32_e32 vcc, 0, v8
	v_add_u32_e32 v8, 1, v10
	v_fma_f32 v9, -v8, v10, v1
	v_cndmask_b32_e32 v0, v10, v0, vcc
	v_cmp_lt_f32_e32 vcc, 0, v9
	v_ashrrev_i32_e32 v73, 31, v72
	v_ashrrev_i32_e32 v71, 31, v70
	v_cndmask_b32_e32 v0, v0, v8, vcc
	v_mul_f32_e32 v8, 0x37800000, v0
	v_cndmask_b32_e64 v0, v0, v8, s[0:1]
	v_cmp_class_f32_e32 vcc, v1, v84
	s_nop 1
	v_cndmask_b32_e32 v8, v0, v1, vcc
	v_div_scale_f32 v9, s[0:1], v8, v8, v5
	v_rcp_f32_e32 v10, v9
	v_lshlrev_b64 v[0:1], 6, v[76:77]
	v_lshl_add_u64 v[0:1], v[68:69], 0, v[0:1]
	global_store_dword v[0:1], v4, off
	v_fma_f32 v0, -v9, v10, 1.0
	v_fmac_f32_e32 v10, v0, v10
	v_div_scale_f32 v0, vcc, v5, v8, v5
	v_mul_f32_e32 v1, v0, v10
	v_fma_f32 v4, -v9, v1, v0
	v_fmac_f32_e32 v1, v4, v10
	v_mul_f32_e32 v4, 0x4f800000, v2
	v_cmp_gt_f32_e64 s[0:1], s6, v2
	v_fma_f32 v0, -v9, v1, v0
	v_div_fmas_f32 v0, v0, v10, v1
	v_cndmask_b32_e64 v2, v2, v4, s[0:1]
	v_sqrt_f32_e32 v4, v2
	v_div_fixup_f32 v5, v0, v8, v5
	v_add_u32_e32 v0, -1, v4
	v_fma_f32 v1, -v0, v4, v2
	v_cmp_ge_f32_e32 vcc, 0, v1
	v_add_u32_e32 v1, 1, v4
	s_nop 0
	v_cndmask_b32_e32 v0, v4, v0, vcc
	v_fma_f32 v4, -v1, v4, v2
	v_cmp_lt_f32_e32 vcc, 0, v4
	s_nop 1
	v_cndmask_b32_e32 v0, v0, v1, vcc
	v_mul_f32_e32 v1, 0x37800000, v0
	v_cndmask_b32_e64 v0, v0, v1, s[0:1]
	v_cmp_class_f32_e32 vcc, v2, v84
	s_nop 1
	v_cndmask_b32_e32 v2, v0, v2, vcc
	v_div_scale_f32 v4, s[0:1], v2, v2, v6
	v_rcp_f32_e32 v8, v4
	v_lshlrev_b64 v[0:1], 6, v[74:75]
	v_lshl_add_u64 v[0:1], v[68:69], 0, v[0:1]
	global_store_dword v[0:1], v5, off
	v_fma_f32 v0, -v4, v8, 1.0
	v_fmac_f32_e32 v8, v0, v8
	v_div_scale_f32 v0, vcc, v6, v2, v6
	v_mul_f32_e32 v1, v0, v8
	v_fma_f32 v5, -v4, v1, v0
	v_fmac_f32_e32 v1, v5, v8
	v_fma_f32 v0, -v4, v1, v0
	v_mul_f32_e32 v4, 0x4f800000, v3
	v_cmp_gt_f32_e64 s[0:1], s6, v3
	v_div_fmas_f32 v0, v0, v8, v1
	v_div_fixup_f32 v2, v0, v2, v6
	v_cndmask_b32_e64 v3, v3, v4, s[0:1]
	v_sqrt_f32_e32 v4, v3
	s_nop 0
	v_add_u32_e32 v0, -1, v4
	v_fma_f32 v1, -v0, v4, v3
	v_cmp_ge_f32_e32 vcc, 0, v1
	v_add_u32_e32 v1, 1, v4
	s_nop 0
	v_cndmask_b32_e32 v0, v4, v0, vcc
	v_fma_f32 v4, -v1, v4, v3
	v_cmp_lt_f32_e32 vcc, 0, v4
	s_nop 1
	v_cndmask_b32_e32 v0, v0, v1, vcc
	v_mul_f32_e32 v1, 0x37800000, v0
	v_cndmask_b32_e64 v0, v0, v1, s[0:1]
	v_cmp_class_f32_e32 vcc, v3, v84
	s_nop 1
	v_cndmask_b32_e32 v3, v0, v3, vcc
	v_div_scale_f32 v4, s[0:1], v3, v3, v7
	v_rcp_f32_e32 v5, v4
	v_lshlrev_b64 v[0:1], 6, v[72:73]
	v_lshl_add_u64 v[0:1], v[68:69], 0, v[0:1]
	global_store_dword v[0:1], v2, off
	v_fma_f32 v0, -v4, v5, 1.0
	v_fmac_f32_e32 v5, v0, v5
	v_div_scale_f32 v0, vcc, v7, v3, v7
	v_mul_f32_e32 v1, v0, v5
	v_fma_f32 v2, -v4, v1, v0
	v_fmac_f32_e32 v1, v2, v5
	v_fma_f32 v0, -v4, v1, v0
	v_div_fmas_f32 v0, v0, v5, v1
	v_div_fixup_f32 v2, v0, v3, v7
	v_lshlrev_b64 v[0:1], 6, v[70:71]
	v_lshl_add_u64 v[0:1], v[68:69], 0, v[0:1]
	global_store_dword v[0:1], v2, off
	s_branch .LBB0_1190
